# speedup vs baseline: 1.0053x; 1.0053x over previous
.LBB0_101:
	s_or_b64 exec, exec, s[12:13]
	s_waitcnt vmcnt(0)
	v_add_f32_e32 v1, v18, v19
	v_add_f32_e32 v1, v20, v1
	v_add_f32_e32 v1, v21, v1
	v_fmamk_f32 v1, v1, 0x3a800000, v208
	v_mul_f32_e32 v18, 0x4b800000, v1
	v_cmp_gt_f32_e64 s[4:5], s95, v1
	s_waitcnt vmcnt(3)
	v_lshlrev_b32_e32 v20, 16, v47
	v_and_b32_e32 v21, 0xffff0000, v47
	v_cndmask_b32_e64 v1, v1, v18, s[4:5]
	v_rsq_f32_e32 v1, v1
	v_lshlrev_b64 v[18:19], 12, v[36:37]
	v_lshl_add_u64 v[36:37], v[24:25], 0, v[18:19]
	v_and_b32_e32 v19, 0xffff0000, v46
	v_mul_f32_e32 v18, 0x45800000, v1
	v_cndmask_b32_e64 v48, v1, v18, s[4:5]
	v_lshlrev_b32_e32 v18, 16, v46
	v_pk_mul_f32 v[18:19], v[48:49], v[18:19] op_sel_hi:[0,1]
	v_pk_mul_f32 v[20:21], v[48:49], v[20:21] op_sel_hi:[0,1]
	v_pk_mul_f32 v[18:19], v[14:15], v[18:19]
	v_pk_mul_f32 v[20:21], v[16:17], v[20:21]
	global_store_dwordx4 v[36:37], v[18:21], off nt
	s_waitcnt vmcnt(3)
	s_nop 0
	v_lshlrev_b32_e32 v18, 16, v44
	v_and_b32_e32 v19, 0xffff0000, v44
	v_lshlrev_b32_e32 v20, 16, v45
	v_and_b32_e32 v21, 0xffff0000, v45
	v_pk_mul_f32 v[18:19], v[48:49], v[18:19] op_sel_hi:[0,1]
	v_pk_mul_f32 v[20:21], v[48:49], v[20:21] op_sel_hi:[0,1]
	v_pk_mul_f32 v[18:19], v[10:11], v[18:19]
	v_pk_mul_f32 v[20:21], v[12:13], v[20:21]
	global_store_dwordx4 v[36:37], v[18:21], off offset:1024 nt
	s_waitcnt vmcnt(3)
	s_nop 0
	v_lshlrev_b32_e32 v18, 16, v40
	v_and_b32_e32 v19, 0xffff0000, v40
	v_lshlrev_b32_e32 v20, 16, v41
	v_and_b32_e32 v21, 0xffff0000, v41
	v_pk_mul_f32 v[18:19], v[48:49], v[18:19] op_sel_hi:[0,1]
	v_pk_mul_f32 v[20:21], v[48:49], v[20:21] op_sel_hi:[0,1]
	v_pk_mul_f32 v[18:19], v[6:7], v[18:19]
	v_pk_mul_f32 v[20:21], v[8:9], v[20:21]
	global_store_dwordx4 v[36:37], v[18:21], off offset:2048 nt
	s_waitcnt vmcnt(3)
	s_nop 0
	v_lshlrev_b32_e32 v18, 16, v38
	v_and_b32_e32 v19, 0xffff0000, v38
	v_lshlrev_b32_e32 v20, 16, v39
	v_and_b32_e32 v21, 0xffff0000, v39
	v_pk_mul_f32 v[18:19], v[48:49], v[18:19] op_sel_hi:[0,1]
	v_pk_mul_f32 v[20:21], v[48:49], v[20:21] op_sel_hi:[0,1]
	v_pk_mul_f32 v[18:19], v[2:3], v[18:19]
	v_pk_mul_f32 v[20:21], v[4:5], v[20:21]
	global_store_dwordx4 v[36:37], v[18:21], off offset:3072 nt
	s_and_saveexec_b64 s[4:5], vcc
	s_cbranch_execz .LBB0_98
	v_lshlrev_b64 v[18:19], 12, v[30:31]
	v_lshl_add_u64 v[36:37], v[24:25], 0, v[18:19]
	v_lshlrev_b32_e32 v18, 16, v26
	v_and_b32_e32 v19, 0xffff0000, v26
	v_lshlrev_b32_e32 v20, 16, v27
	v_and_b32_e32 v21, 0xffff0000, v27
	v_pk_mul_f32 v[18:19], v[42:43], v[18:19] op_sel_hi:[0,1]
	v_pk_mul_f32 v[20:21], v[42:43], v[20:21] op_sel_hi:[0,1]
	v_pk_mul_f32 v[18:19], v[14:15], v[18:19]
	v_pk_mul_f32 v[20:21], v[16:17], v[20:21]
	global_store_dwordx4 v[36:37], v[18:21], off nt
	s_nop 1
	v_lshlrev_b32_e32 v18, 16, v28
	v_and_b32_e32 v19, 0xffff0000, v28
	v_lshlrev_b32_e32 v20, 16, v29
	v_and_b32_e32 v21, 0xffff0000, v29
	v_pk_mul_f32 v[18:19], v[42:43], v[18:19] op_sel_hi:[0,1]
	v_pk_mul_f32 v[20:21], v[42:43], v[20:21] op_sel_hi:[0,1]
	v_pk_mul_f32 v[18:19], v[10:11], v[18:19]
	v_pk_mul_f32 v[20:21], v[12:13], v[20:21]
	global_store_dwordx4 v[36:37], v[18:21], off offset:1024 nt
	s_nop 1
	v_lshlrev_b32_e32 v18, 16, v32
	v_and_b32_e32 v19, 0xffff0000, v32
	v_lshlrev_b32_e32 v20, 16, v33
	v_and_b32_e32 v21, 0xffff0000, v33
	v_pk_mul_f32 v[18:19], v[42:43], v[18:19] op_sel_hi:[0,1]
	v_pk_mul_f32 v[20:21], v[42:43], v[20:21] op_sel_hi:[0,1]
	v_pk_mul_f32 v[18:19], v[6:7], v[18:19]
	v_pk_mul_f32 v[20:21], v[8:9], v[20:21]
	global_store_dwordx4 v[36:37], v[18:21], off offset:2048 nt
	s_nop 1
	v_lshlrev_b32_e32 v18, 16, v34
	v_and_b32_e32 v19, 0xffff0000, v34
	v_lshlrev_b32_e32 v20, 16, v35
	v_and_b32_e32 v21, 0xffff0000, v35
	v_pk_mul_f32 v[18:19], v[42:43], v[18:19] op_sel_hi:[0,1]
	v_pk_mul_f32 v[20:21], v[42:43], v[20:21] op_sel_hi:[0,1]
	v_pk_mul_f32 v[18:19], v[2:3], v[18:19]
	v_pk_mul_f32 v[20:21], v[4:5], v[20:21]
	global_store_dwordx4 v[36:37], v[18:21], off offset:3072 nt
	s_branch .LBB0_98
